# in-proj/out-proj GEMM K-loops: hipcc's per-MFMA-block s_setprio 1/0 flips deleted (A/B)
# speedup vs baseline: 1.0105x; 1.0105x over previous
.LBB0_28:
	s_add_u32 s8, s56, 0xfff80080
	s_addc_u32 s12, s57, -1
	s_add_i32 s20, 0, 0x10000
	s_cmp_eq_u32 s63, 28
	s_cselect_b32 s13, s47, s12
	s_cselect_b32 s12, s51, s8
	v_add_u32_e32 v138, s20, v141
	v_add_u32_e32 v238, s20, v241
	s_cselect_b32 s59, s45, s62
	s_cselect_b32 s58, s60, s61
	s_add_i32 s8, 0, 0x14000
	ds_read_b128 v[144:147], v138
	ds_read_b128 v[148:151], v238
	ds_read_b128 v[152:155], v138 offset:2048
	ds_read_b128 v[156:159], v238 offset:2048
	v_add_u32_e32 v138, s8, v141
	v_add_u32_e32 v238, s8, v241
	ds_read_b128 v[160:163], v138
	ds_read_b128 v[164:167], v238
	ds_read_b128 v[168:171], v138 offset:2048
	ds_read_b128 v[172:175], v238 offset:2048
	v_lshl_add_u64 v[138:139], s[56:57], 0, v[134:135]
	s_add_i32 m0, s31, 0xc000
	ds_read_b128 v[176:179], v143
	ds_read_b128 v[180:183], v240
	ds_read_b128 v[186:189], v143 offset:2048
	ds_read_b128 v[192:195], v240 offset:2048
	ds_read_b128 v[196:199], v143 offset:4096
	ds_read_b128 v[214:217], v240 offset:4096
	ds_read_b128 v[218:221], v143 offset:6144
	ds_read_b128 v[222:225], v240 offset:6144
	global_load_lds_dwordx4 v[138:139], off
	v_lshl_add_u64 v[138:139], s[56:57], 0, v[136:137]
	s_add_i32 m0, s31, 0xe000
	s_nop 0
	global_load_lds_dwordx4 v[138:139], off
	s_waitcnt vmcnt(8)
	s_waitcnt lgkmcnt(0)
	s_barrier
	s_waitcnt lgkmcnt(0)
	v_mfma_f32_16x16x32_bf16 v[124:127], v[144:147], v[176:179], v[124:127]
	v_mfma_f32_16x16x32_bf16 v[120:123], v[152:155], v[176:179], v[120:123]
	v_mfma_f32_16x16x32_bf16 v[116:119], v[144:147], v[186:189], v[116:119]
	v_mfma_f32_16x16x32_bf16 v[108:111], v[152:155], v[186:189], v[108:111]
	v_mfma_f32_16x16x32_bf16 v[100:103], v[144:147], v[196:199], v[100:103]
	v_mfma_f32_16x16x32_bf16 v[92:95], v[152:155], v[196:199], v[92:95]
	v_mfma_f32_16x16x32_bf16 v[84:87], v[144:147], v[218:221], v[84:87]
	v_mfma_f32_16x16x32_bf16 v[76:79], v[152:155], v[218:221], v[76:79]
	v_mfma_f32_16x16x32_bf16 v[124:127], v[148:151], v[180:183], v[124:127]
	v_mfma_f32_16x16x32_bf16 v[120:123], v[156:159], v[180:183], v[120:123]
	v_mfma_f32_16x16x32_bf16 v[116:119], v[148:151], v[192:195], v[116:119]
	v_mfma_f32_16x16x32_bf16 v[108:111], v[156:159], v[192:195], v[108:111]
	v_mfma_f32_16x16x32_bf16 v[100:103], v[148:151], v[214:217], v[100:103]
	v_mfma_f32_16x16x32_bf16 v[92:95], v[156:159], v[214:217], v[92:95]
	v_mfma_f32_16x16x32_bf16 v[84:87], v[148:151], v[222:225], v[84:87]
	v_mfma_f32_16x16x32_bf16 v[76:79], v[156:159], v[222:225], v[76:79]
	v_mfma_f32_16x16x32_bf16 v[112:115], v[160:163], v[176:179], v[112:115]
	v_mfma_f32_16x16x32_bf16 v[104:107], v[168:171], v[176:179], v[104:107]
	v_mfma_f32_16x16x32_bf16 v[96:99], v[160:163], v[186:189], v[96:99]
	v_mfma_f32_16x16x32_bf16 v[88:91], v[168:171], v[186:189], v[88:91]
	v_mfma_f32_16x16x32_bf16 v[80:83], v[160:163], v[196:199], v[80:83]
	v_mfma_f32_16x16x32_bf16 v[72:75], v[168:171], v[196:199], v[72:75]
	v_mfma_f32_16x16x32_bf16 v[68:71], v[160:163], v[218:221], v[68:71]
	v_mfma_f32_16x16x32_bf16 v[64:67], v[168:171], v[218:221], v[64:67]
	v_mfma_f32_16x16x32_bf16 v[112:115], v[164:167], v[180:183], v[112:115]
	v_mfma_f32_16x16x32_bf16 v[104:107], v[172:175], v[180:183], v[104:107]
	v_mfma_f32_16x16x32_bf16 v[96:99], v[164:167], v[192:195], v[96:99]
	v_mfma_f32_16x16x32_bf16 v[88:91], v[172:175], v[192:195], v[88:91]
	v_mfma_f32_16x16x32_bf16 v[80:83], v[164:167], v[214:217], v[80:83]
	v_mfma_f32_16x16x32_bf16 v[72:75], v[172:175], v[214:217], v[72:75]
	v_mfma_f32_16x16x32_bf16 v[68:71], v[164:167], v[222:225], v[68:71]
	v_mfma_f32_16x16x32_bf16 v[64:67], v[172:175], v[222:225], v[64:67]
	s_barrier
	s_add_i32 s20, s20, s30
	v_lshl_add_u64 v[138:139], s[58:59], 0, v[184:185]
	s_mov_b32 m0, s20
	ds_read_b128 v[176:179], v143 offset:16384
	ds_read_b128 v[180:183], v240 offset:16384
	ds_read_b128 v[186:189], v143 offset:18432
	ds_read_b128 v[192:195], v240 offset:18432
	ds_read_b128 v[196:199], v143 offset:20480
	ds_read_b128 v[214:217], v240 offset:20480
	ds_read_b128 v[218:221], v143 offset:22528
	ds_read_b128 v[222:225], v240 offset:22528
	global_load_lds_dwordx4 v[138:139], off
	s_add_i32 m0, s20, 0x2000
	s_add_u32 s20, s58, 0x80000
	v_lshl_add_u64 v[200:201], s[58:59], 0, v[128:129]
	s_addc_u32 s21, s59, 0
	s_add_i32 s8, s8, s30
	global_load_lds_dwordx4 v[200:201], off
	v_lshl_add_u64 v[226:227], s[20:21], 0, v[184:185]
	s_mov_b32 m0, s8
	v_lshl_add_u64 v[228:229], s[12:13], 0, v[130:131]
	global_load_lds_dwordx4 v[226:227], off
	v_lshl_add_u64 v[226:227], s[20:21], 0, v[128:129]
	s_add_i32 m0, s8, 0x2000
	s_nop 0
	global_load_lds_dwordx4 v[226:227], off
	v_lshl_add_u64 v[226:227], s[12:13], 0, v[132:133]
	s_mov_b32 m0, s31
	s_nop 0
	global_load_lds_dwordx4 v[226:227], off
	s_mov_b32 m0, s34
	s_nop 0
	global_load_lds_dwordx4 v[228:229], off
	s_waitcnt vmcnt(8)
	s_waitcnt lgkmcnt(0)
	s_barrier
	s_waitcnt lgkmcnt(0)
	v_mfma_f32_16x16x32_bf16 v[60:63], v[144:147], v[176:179], v[60:63]
	v_mfma_f32_16x16x32_bf16 v[56:59], v[152:155], v[176:179], v[56:59]
	v_mfma_f32_16x16x32_bf16 v[52:55], v[144:147], v[186:189], v[52:55]
	v_mfma_f32_16x16x32_bf16 v[44:47], v[152:155], v[186:189], v[44:47]
	v_mfma_f32_16x16x32_bf16 v[36:39], v[144:147], v[196:199], v[36:39]
	v_mfma_f32_16x16x32_bf16 v[28:31], v[152:155], v[196:199], v[28:31]
	v_mfma_f32_16x16x32_bf16 v[20:23], v[144:147], v[218:221], v[20:23]
	v_mfma_f32_16x16x32_bf16 v[12:15], v[152:155], v[218:221], v[12:15]
	v_mfma_f32_16x16x32_bf16 v[60:63], v[148:151], v[180:183], v[60:63]
	v_mfma_f32_16x16x32_bf16 v[56:59], v[156:159], v[180:183], v[56:59]
	v_mfma_f32_16x16x32_bf16 v[52:55], v[148:151], v[192:195], v[52:55]
	v_mfma_f32_16x16x32_bf16 v[44:47], v[156:159], v[192:195], v[44:47]
	v_mfma_f32_16x16x32_bf16 v[36:39], v[148:151], v[214:217], v[36:39]
	v_mfma_f32_16x16x32_bf16 v[28:31], v[156:159], v[214:217], v[28:31]
	v_mfma_f32_16x16x32_bf16 v[20:23], v[148:151], v[222:225], v[20:23]
	v_mfma_f32_16x16x32_bf16 v[12:15], v[156:159], v[222:225], v[12:15]
	v_mfma_f32_16x16x32_bf16 v[48:51], v[160:163], v[176:179], v[48:51]
	v_mfma_f32_16x16x32_bf16 v[40:43], v[168:171], v[176:179], v[40:43]
	v_mfma_f32_16x16x32_bf16 v[32:35], v[160:163], v[186:189], v[32:35]
	v_mfma_f32_16x16x32_bf16 v[24:27], v[168:171], v[186:189], v[24:27]
	v_mfma_f32_16x16x32_bf16 v[16:19], v[160:163], v[196:199], v[16:19]
	v_mfma_f32_16x16x32_bf16 v[8:11], v[168:171], v[196:199], v[8:11]
	v_mfma_f32_16x16x32_bf16 v[4:7], v[160:163], v[218:221], v[4:7]
	v_mfma_f32_16x16x32_bf16 v[0:3], v[168:171], v[218:221], v[0:3]
	v_mfma_f32_16x16x32_bf16 v[48:51], v[164:167], v[180:183], v[48:51]
	v_mfma_f32_16x16x32_bf16 v[40:43], v[172:175], v[180:183], v[40:43]
	v_mfma_f32_16x16x32_bf16 v[32:35], v[164:167], v[192:195], v[32:35]
	v_mfma_f32_16x16x32_bf16 v[24:27], v[172:175], v[192:195], v[24:27]
	v_mfma_f32_16x16x32_bf16 v[16:19], v[164:167], v[214:217], v[16:19]
	v_mfma_f32_16x16x32_bf16 v[8:11], v[172:175], v[214:217], v[8:11]
	v_mfma_f32_16x16x32_bf16 v[4:7], v[164:167], v[222:225], v[4:7]
	v_mfma_f32_16x16x32_bf16 v[0:3], v[172:175], v[222:225], v[0:3]
	s_barrier
	s_add_i32 s8, 0, 0x18000
	s_add_i32 s20, 0, 0x1c000
	v_add_u32_e32 v156, s8, v141
	v_add_u32_e32 v238, s8, v241
	v_add_u32_e32 v172, s20, v141
	v_add_u32_e32 v239, s20, v241
	ds_read_b128 v[144:147], v156
	ds_read_b128 v[148:151], v238
	ds_read_b128 v[152:155], v156 offset:2048
	ds_read_b128 v[156:159], v238 offset:2048
	ds_read_b128 v[160:163], v172
	ds_read_b128 v[164:167], v239
	ds_read_b128 v[168:171], v172 offset:2048
	ds_read_b128 v[172:175], v239 offset:2048
	s_add_u32 s12, s12, 0x80000
	s_addc_u32 s13, s13, 0
	s_mov_b32 m0, s35
	v_lshl_add_u64 v[230:231], s[12:13], 0, v[132:133]
	ds_read_b128 v[176:179], v143 offset:32768
	ds_read_b128 v[180:183], v240 offset:32768
	ds_read_b128 v[186:189], v143 offset:34816
	ds_read_b128 v[192:195], v240 offset:34816
	ds_read_b128 v[196:199], v143 offset:36864
	ds_read_b128 v[214:217], v240 offset:36864
	ds_read_b128 v[218:221], v143 offset:38912
	ds_read_b128 v[222:225], v240 offset:38912
	global_load_lds_dwordx4 v[230:231], off
	v_lshl_add_u64 v[230:231], s[12:13], 0, v[130:131]
	s_mov_b32 m0, s36
	s_nop 0
	global_load_lds_dwordx4 v[230:231], off
	s_waitcnt vmcnt(8)
	s_waitcnt lgkmcnt(0)
	s_barrier
	s_waitcnt lgkmcnt(0)
	v_mfma_f32_16x16x32_bf16 v[124:127], v[144:147], v[176:179], v[124:127]
	v_mfma_f32_16x16x32_bf16 v[120:123], v[152:155], v[176:179], v[120:123]
	v_mfma_f32_16x16x32_bf16 v[116:119], v[144:147], v[186:189], v[116:119]
	v_mfma_f32_16x16x32_bf16 v[108:111], v[152:155], v[186:189], v[108:111]
	v_mfma_f32_16x16x32_bf16 v[100:103], v[144:147], v[196:199], v[100:103]
	v_mfma_f32_16x16x32_bf16 v[92:95], v[152:155], v[196:199], v[92:95]
	v_mfma_f32_16x16x32_bf16 v[84:87], v[144:147], v[218:221], v[84:87]
	v_mfma_f32_16x16x32_bf16 v[76:79], v[152:155], v[218:221], v[76:79]
	v_mfma_f32_16x16x32_bf16 v[124:127], v[148:151], v[180:183], v[124:127]
	v_mfma_f32_16x16x32_bf16 v[120:123], v[156:159], v[180:183], v[120:123]
	v_mfma_f32_16x16x32_bf16 v[116:119], v[148:151], v[192:195], v[116:119]
	v_mfma_f32_16x16x32_bf16 v[108:111], v[156:159], v[192:195], v[108:111]
	v_mfma_f32_16x16x32_bf16 v[100:103], v[148:151], v[214:217], v[100:103]
	v_mfma_f32_16x16x32_bf16 v[92:95], v[156:159], v[214:217], v[92:95]
	v_mfma_f32_16x16x32_bf16 v[84:87], v[148:151], v[222:225], v[84:87]
	v_mfma_f32_16x16x32_bf16 v[76:79], v[156:159], v[222:225], v[76:79]
	v_mfma_f32_16x16x32_bf16 v[112:115], v[160:163], v[176:179], v[112:115]
	v_mfma_f32_16x16x32_bf16 v[104:107], v[168:171], v[176:179], v[104:107]
	v_mfma_f32_16x16x32_bf16 v[96:99], v[160:163], v[186:189], v[96:99]
	v_mfma_f32_16x16x32_bf16 v[88:91], v[168:171], v[186:189], v[88:91]
	v_mfma_f32_16x16x32_bf16 v[80:83], v[160:163], v[196:199], v[80:83]
	v_mfma_f32_16x16x32_bf16 v[72:75], v[168:171], v[196:199], v[72:75]
	v_mfma_f32_16x16x32_bf16 v[68:71], v[160:163], v[218:221], v[68:71]
	v_mfma_f32_16x16x32_bf16 v[64:67], v[168:171], v[218:221], v[64:67]
	v_mfma_f32_16x16x32_bf16 v[112:115], v[164:167], v[180:183], v[112:115]
	v_mfma_f32_16x16x32_bf16 v[104:107], v[172:175], v[180:183], v[104:107]
	v_mfma_f32_16x16x32_bf16 v[96:99], v[164:167], v[192:195], v[96:99]
	v_mfma_f32_16x16x32_bf16 v[88:91], v[172:175], v[192:195], v[88:91]
	v_mfma_f32_16x16x32_bf16 v[80:83], v[164:167], v[214:217], v[80:83]
	v_mfma_f32_16x16x32_bf16 v[72:75], v[172:175], v[214:217], v[72:75]
	v_mfma_f32_16x16x32_bf16 v[68:71], v[164:167], v[222:225], v[68:71]
	v_mfma_f32_16x16x32_bf16 v[64:67], v[172:175], v[222:225], v[64:67]
	s_barrier
	s_add_i32 s8, s8, s30
	v_lshl_add_u64 v[138:139], v[138:139], 0, s[26:27]
	s_mov_b32 m0, s8
	ds_read_b128 v[176:179], v143 offset:49152
	ds_read_b128 v[180:183], v240 offset:49152
	ds_read_b128 v[186:189], v143 offset:51200
	ds_read_b128 v[192:195], v240 offset:51200
	ds_read_b128 v[196:199], v143 offset:53248
	ds_read_b128 v[214:217], v240 offset:53248
	ds_read_b128 v[218:221], v143 offset:55296
	ds_read_b128 v[222:225], v240 offset:55296
	global_load_lds_dwordx4 v[138:139], off
	s_add_i32 m0, s8, 0x2000
	s_add_u32 s12, s58, 0x80080
	v_lshl_add_u64 v[138:139], v[200:201], 0, s[26:27]
	s_addc_u32 s13, s59, 0
	s_add_i32 s8, s20, s30
	global_load_lds_dwordx4 v[138:139], off
	v_lshl_add_u64 v[138:139], s[12:13], 0, v[184:185]
	s_mov_b32 m0, s8
	s_nop 0
	global_load_lds_dwordx4 v[138:139], off
	v_lshl_add_u64 v[138:139], s[12:13], 0, v[128:129]
	s_add_i32 m0, s8, 0x2000
	s_nop 0
	global_load_lds_dwordx4 v[138:139], off
	v_lshl_add_u64 v[138:139], v[226:227], 0, s[26:27]
	s_mov_b32 m0, s38
	s_nop 0
	global_load_lds_dwordx4 v[138:139], off
	v_lshl_add_u64 v[138:139], v[228:229], 0, s[26:27]
	s_mov_b32 m0, s39
	s_nop 0
	global_load_lds_dwordx4 v[138:139], off
	s_waitcnt vmcnt(8)
	s_waitcnt lgkmcnt(0)
	s_barrier
	s_waitcnt lgkmcnt(0)
	v_mfma_f32_16x16x32_bf16 v[60:63], v[144:147], v[176:179], v[60:63]
	v_mfma_f32_16x16x32_bf16 v[56:59], v[152:155], v[176:179], v[56:59]
	v_mfma_f32_16x16x32_bf16 v[52:55], v[144:147], v[186:189], v[52:55]
	v_mfma_f32_16x16x32_bf16 v[44:47], v[152:155], v[186:189], v[44:47]
	v_mfma_f32_16x16x32_bf16 v[36:39], v[144:147], v[196:199], v[36:39]
	v_mfma_f32_16x16x32_bf16 v[28:31], v[152:155], v[196:199], v[28:31]
	v_mfma_f32_16x16x32_bf16 v[20:23], v[144:147], v[218:221], v[20:23]
	v_mfma_f32_16x16x32_bf16 v[12:15], v[152:155], v[218:221], v[12:15]
	v_mfma_f32_16x16x32_bf16 v[60:63], v[148:151], v[180:183], v[60:63]
	v_mfma_f32_16x16x32_bf16 v[56:59], v[156:159], v[180:183], v[56:59]
	v_mfma_f32_16x16x32_bf16 v[52:55], v[148:151], v[192:195], v[52:55]
	v_mfma_f32_16x16x32_bf16 v[44:47], v[156:159], v[192:195], v[44:47]
	v_mfma_f32_16x16x32_bf16 v[36:39], v[148:151], v[214:217], v[36:39]
	v_mfma_f32_16x16x32_bf16 v[28:31], v[156:159], v[214:217], v[28:31]
	v_mfma_f32_16x16x32_bf16 v[20:23], v[148:151], v[222:225], v[20:23]
	v_mfma_f32_16x16x32_bf16 v[12:15], v[156:159], v[222:225], v[12:15]
	v_mfma_f32_16x16x32_bf16 v[48:51], v[160:163], v[176:179], v[48:51]
	v_mfma_f32_16x16x32_bf16 v[40:43], v[168:171], v[176:179], v[40:43]
	v_mfma_f32_16x16x32_bf16 v[32:35], v[160:163], v[186:189], v[32:35]
	v_mfma_f32_16x16x32_bf16 v[24:27], v[168:171], v[186:189], v[24:27]
	v_mfma_f32_16x16x32_bf16 v[16:19], v[160:163], v[196:199], v[16:19]
	v_mfma_f32_16x16x32_bf16 v[8:11], v[168:171], v[196:199], v[8:11]
	v_mfma_f32_16x16x32_bf16 v[4:7], v[160:163], v[218:221], v[4:7]
	v_mfma_f32_16x16x32_bf16 v[0:3], v[168:171], v[218:221], v[0:3]
	v_mfma_f32_16x16x32_bf16 v[48:51], v[164:167], v[180:183], v[48:51]
	v_mfma_f32_16x16x32_bf16 v[40:43], v[172:175], v[180:183], v[40:43]
	v_mfma_f32_16x16x32_bf16 v[32:35], v[164:167], v[192:195], v[32:35]
	v_mfma_f32_16x16x32_bf16 v[24:27], v[172:175], v[192:195], v[24:27]
	v_mfma_f32_16x16x32_bf16 v[16:19], v[164:167], v[214:217], v[16:19]
	v_mfma_f32_16x16x32_bf16 v[8:11], v[172:175], v[214:217], v[8:11]
	v_mfma_f32_16x16x32_bf16 v[4:7], v[164:167], v[222:225], v[4:7]
	v_mfma_f32_16x16x32_bf16 v[0:3], v[172:175], v[222:225], v[0:3]
	s_barrier
	s_add_i32 s63, s63, 2
	s_add_u32 s56, s56, 0x100
	s_addc_u32 s57, s57, 0
	s_add_u32 s61, s61, 0x100
	s_addc_u32 s62, s62, 0
	s_cmp_gt_u32 s63, 29
	s_cbranch_scc0 .LBB0_28
	s_and_b64 vcc, exec, s[42:43]
	s_cbranch_vccz .LBB0_31
	s_barrier

.LBB0_182:
	s_add_u32 s8, s14, 0xfff80080
	s_addc_u32 s12, s15, -1
	s_add_i32 s20, 0, 0x10000
	s_cmp_eq_u32 s51, 28
	s_cselect_b32 s13, s37, s12
	s_cselect_b32 s12, s46, s8
	s_cselect_b32 s45, s47, s50
	s_cselect_b32 s44, s48, s49
	s_add_i32 s8, 0, 0x14000
	v_add_u32_e32 v154, s20, v147
	v_add_u32_e32 v238, s20, v241
	v_add_u32_e32 v170, s8, v147
	v_add_u32_e32 v239, s8, v241
	ds_read_b128 v[138:141], v154
	ds_read_b128 v[142:145], v238
	ds_read_b128 v[150:153], v154 offset:2048
	ds_read_b128 v[154:157], v238 offset:2048
	ds_read_b128 v[158:161], v170
	ds_read_b128 v[162:165], v239
	ds_read_b128 v[166:169], v170 offset:2048
	ds_read_b128 v[170:173], v239 offset:2048
	v_lshl_add_u64 v[182:183], s[14:15], 0, v[134:135]
	s_add_i32 m0, s30, 0xc000
	ds_read_b128 v[174:177], v149
	ds_read_b128 v[178:181], v240
	ds_read_b128 v[192:195], v149 offset:2048
	ds_read_b128 v[196:199], v240 offset:2048
	ds_read_b128 v[214:217], v149 offset:4096
	ds_read_b128 v[218:221], v240 offset:4096
	ds_read_b128 v[222:225], v149 offset:6144
	ds_read_b128 v[226:229], v240 offset:6144
	global_load_lds_dwordx4 v[182:183], off
	v_lshl_add_u64 v[182:183], s[14:15], 0, v[136:137]
	s_add_i32 m0, s30, 0xe000
	s_nop 0
	global_load_lds_dwordx4 v[182:183], off
	s_waitcnt vmcnt(8)
	s_waitcnt lgkmcnt(0)
	s_barrier
	s_waitcnt lgkmcnt(0)
	v_mfma_f32_16x16x32_bf16 v[124:127], v[138:141], v[174:177], v[124:127]
	v_mfma_f32_16x16x32_bf16 v[120:123], v[150:153], v[174:177], v[120:123]
	v_mfma_f32_16x16x32_bf16 v[108:111], v[138:141], v[192:195], v[108:111]
	v_mfma_f32_16x16x32_bf16 v[104:107], v[150:153], v[192:195], v[104:107]
	v_mfma_f32_16x16x32_bf16 v[92:95], v[138:141], v[214:217], v[92:95]
	v_mfma_f32_16x16x32_bf16 v[88:91], v[150:153], v[214:217], v[88:91]
	v_mfma_f32_16x16x32_bf16 v[76:79], v[138:141], v[222:225], v[76:79]
	v_mfma_f32_16x16x32_bf16 v[72:75], v[150:153], v[222:225], v[72:75]
	v_mfma_f32_16x16x32_bf16 v[124:127], v[142:145], v[178:181], v[124:127]
	v_mfma_f32_16x16x32_bf16 v[120:123], v[154:157], v[178:181], v[120:123]
	v_mfma_f32_16x16x32_bf16 v[108:111], v[142:145], v[196:199], v[108:111]
	v_mfma_f32_16x16x32_bf16 v[104:107], v[154:157], v[196:199], v[104:107]
	v_mfma_f32_16x16x32_bf16 v[92:95], v[142:145], v[218:221], v[92:95]
	v_mfma_f32_16x16x32_bf16 v[88:91], v[154:157], v[218:221], v[88:91]
	v_mfma_f32_16x16x32_bf16 v[76:79], v[142:145], v[226:229], v[76:79]
	v_mfma_f32_16x16x32_bf16 v[72:75], v[154:157], v[226:229], v[72:75]
	v_mfma_f32_16x16x32_bf16 v[116:119], v[158:161], v[174:177], v[116:119]
	v_mfma_f32_16x16x32_bf16 v[112:115], v[166:169], v[174:177], v[112:115]
	v_mfma_f32_16x16x32_bf16 v[100:103], v[158:161], v[192:195], v[100:103]
	v_mfma_f32_16x16x32_bf16 v[96:99], v[166:169], v[192:195], v[96:99]
	v_mfma_f32_16x16x32_bf16 v[84:87], v[158:161], v[214:217], v[84:87]
	v_mfma_f32_16x16x32_bf16 v[80:83], v[166:169], v[214:217], v[80:83]
	v_mfma_f32_16x16x32_bf16 v[68:71], v[158:161], v[222:225], v[68:71]
	v_mfma_f32_16x16x32_bf16 v[64:67], v[166:169], v[222:225], v[64:67]
	v_mfma_f32_16x16x32_bf16 v[116:119], v[162:165], v[178:181], v[116:119]
	v_mfma_f32_16x16x32_bf16 v[112:115], v[170:173], v[178:181], v[112:115]
	v_mfma_f32_16x16x32_bf16 v[100:103], v[162:165], v[196:199], v[100:103]
	v_mfma_f32_16x16x32_bf16 v[96:99], v[170:173], v[196:199], v[96:99]
	v_mfma_f32_16x16x32_bf16 v[84:87], v[162:165], v[218:221], v[84:87]
	v_mfma_f32_16x16x32_bf16 v[80:83], v[170:173], v[218:221], v[80:83]
	v_mfma_f32_16x16x32_bf16 v[68:71], v[162:165], v[226:229], v[68:71]
	v_mfma_f32_16x16x32_bf16 v[64:67], v[170:173], v[226:229], v[64:67]
	s_barrier
	s_add_i32 s20, s20, s25
	v_lshl_add_u64 v[182:183], s[44:45], 0, v[184:185]
	s_mov_b32 m0, s20
	ds_read_b128 v[174:177], v149 offset:16384
	ds_read_b128 v[178:181], v240 offset:16384
	ds_read_b128 v[192:195], v149 offset:18432
	ds_read_b128 v[196:199], v240 offset:18432
	ds_read_b128 v[214:217], v149 offset:20480
	ds_read_b128 v[218:221], v240 offset:20480
	ds_read_b128 v[222:225], v149 offset:22528
	ds_read_b128 v[226:229], v240 offset:22528
	global_load_lds_dwordx4 v[182:183], off
	s_add_i32 m0, s20, 0x2000
	s_add_u32 s20, s44, 0x80000
	v_lshl_add_u64 v[186:187], s[44:45], 0, v[128:129]
	s_addc_u32 s21, s45, 0
	s_add_i32 s8, s8, s25
	global_load_lds_dwordx4 v[186:187], off
	v_lshl_add_u64 v[188:189], s[20:21], 0, v[184:185]
	s_mov_b32 m0, s8
	v_lshl_add_u64 v[200:201], s[12:13], 0, v[130:131]
	global_load_lds_dwordx4 v[188:189], off
	v_lshl_add_u64 v[188:189], s[20:21], 0, v[128:129]
	s_add_i32 m0, s8, 0x2000
	s_nop 0
	global_load_lds_dwordx4 v[188:189], off
	v_lshl_add_u64 v[188:189], s[12:13], 0, v[132:133]
	s_mov_b32 m0, s30
	s_nop 0
	global_load_lds_dwordx4 v[188:189], off
	s_mov_b32 m0, s31
	s_nop 0
	global_load_lds_dwordx4 v[200:201], off
	s_waitcnt vmcnt(8)
	s_waitcnt lgkmcnt(0)
	s_barrier
	s_waitcnt lgkmcnt(0)
	v_mfma_f32_16x16x32_bf16 v[60:63], v[138:141], v[174:177], v[60:63]
	v_mfma_f32_16x16x32_bf16 v[56:59], v[150:153], v[174:177], v[56:59]
	v_mfma_f32_16x16x32_bf16 v[44:47], v[138:141], v[192:195], v[44:47]
	v_mfma_f32_16x16x32_bf16 v[40:43], v[150:153], v[192:195], v[40:43]
	v_mfma_f32_16x16x32_bf16 v[28:31], v[138:141], v[214:217], v[28:31]
	v_mfma_f32_16x16x32_bf16 v[24:27], v[150:153], v[214:217], v[24:27]
	v_mfma_f32_16x16x32_bf16 v[12:15], v[138:141], v[222:225], v[12:15]
	v_mfma_f32_16x16x32_bf16 v[8:11], v[150:153], v[222:225], v[8:11]
	v_mfma_f32_16x16x32_bf16 v[60:63], v[142:145], v[178:181], v[60:63]
	v_mfma_f32_16x16x32_bf16 v[56:59], v[154:157], v[178:181], v[56:59]
	v_mfma_f32_16x16x32_bf16 v[44:47], v[142:145], v[196:199], v[44:47]
	v_mfma_f32_16x16x32_bf16 v[40:43], v[154:157], v[196:199], v[40:43]
	v_mfma_f32_16x16x32_bf16 v[28:31], v[142:145], v[218:221], v[28:31]
	v_mfma_f32_16x16x32_bf16 v[24:27], v[154:157], v[218:221], v[24:27]
	v_mfma_f32_16x16x32_bf16 v[12:15], v[142:145], v[226:229], v[12:15]
	v_mfma_f32_16x16x32_bf16 v[8:11], v[154:157], v[226:229], v[8:11]
	v_mfma_f32_16x16x32_bf16 v[52:55], v[158:161], v[174:177], v[52:55]
	v_mfma_f32_16x16x32_bf16 v[48:51], v[166:169], v[174:177], v[48:51]
	v_mfma_f32_16x16x32_bf16 v[36:39], v[158:161], v[192:195], v[36:39]
	v_mfma_f32_16x16x32_bf16 v[32:35], v[166:169], v[192:195], v[32:35]
	v_mfma_f32_16x16x32_bf16 v[20:23], v[158:161], v[214:217], v[20:23]
	v_mfma_f32_16x16x32_bf16 v[16:19], v[166:169], v[214:217], v[16:19]
	v_mfma_f32_16x16x32_bf16 v[4:7], v[158:161], v[222:225], v[4:7]
	v_mfma_f32_16x16x32_bf16 v[0:3], v[166:169], v[222:225], v[0:3]
	v_mfma_f32_16x16x32_bf16 v[52:55], v[162:165], v[178:181], v[52:55]
	v_mfma_f32_16x16x32_bf16 v[48:51], v[170:173], v[178:181], v[48:51]
	v_mfma_f32_16x16x32_bf16 v[36:39], v[162:165], v[196:199], v[36:39]
	v_mfma_f32_16x16x32_bf16 v[32:35], v[170:173], v[196:199], v[32:35]
	v_mfma_f32_16x16x32_bf16 v[20:23], v[162:165], v[218:221], v[20:23]
	v_mfma_f32_16x16x32_bf16 v[16:19], v[170:173], v[218:221], v[16:19]
	v_mfma_f32_16x16x32_bf16 v[4:7], v[162:165], v[226:229], v[4:7]
	v_mfma_f32_16x16x32_bf16 v[0:3], v[170:173], v[226:229], v[0:3]
	s_barrier
	s_add_i32 s8, 0, 0x18000
	s_add_i32 s20, 0, 0x1c000
	v_add_u32_e32 v154, s8, v147
	v_add_u32_e32 v238, s8, v241
	v_add_u32_e32 v170, s20, v147
	v_add_u32_e32 v239, s20, v241
	ds_read_b128 v[138:141], v154
	ds_read_b128 v[142:145], v238
	ds_read_b128 v[150:153], v154 offset:2048
	ds_read_b128 v[154:157], v238 offset:2048
	ds_read_b128 v[158:161], v170
	ds_read_b128 v[162:165], v239
	ds_read_b128 v[166:169], v170 offset:2048
	ds_read_b128 v[170:173], v239 offset:2048
	s_add_u32 s12, s12, 0x80000
	s_addc_u32 s13, s13, 0
	s_mov_b32 m0, s38
	v_lshl_add_u64 v[230:231], s[12:13], 0, v[132:133]
	ds_read_b128 v[174:177], v149 offset:32768
	ds_read_b128 v[178:181], v240 offset:32768
	ds_read_b128 v[192:195], v149 offset:34816
	ds_read_b128 v[196:199], v240 offset:34816
	ds_read_b128 v[214:217], v149 offset:36864
	ds_read_b128 v[218:221], v240 offset:36864
	ds_read_b128 v[222:225], v149 offset:38912
	ds_read_b128 v[226:229], v240 offset:38912
	global_load_lds_dwordx4 v[230:231], off
	v_lshl_add_u64 v[230:231], s[12:13], 0, v[130:131]
	s_mov_b32 m0, s39
	s_nop 0
	global_load_lds_dwordx4 v[230:231], off
	s_waitcnt vmcnt(8)
	s_waitcnt lgkmcnt(0)
	s_barrier
	s_waitcnt lgkmcnt(0)
	v_mfma_f32_16x16x32_bf16 v[124:127], v[138:141], v[174:177], v[124:127]
	v_mfma_f32_16x16x32_bf16 v[120:123], v[150:153], v[174:177], v[120:123]
	v_mfma_f32_16x16x32_bf16 v[108:111], v[138:141], v[192:195], v[108:111]
	v_mfma_f32_16x16x32_bf16 v[104:107], v[150:153], v[192:195], v[104:107]
	v_mfma_f32_16x16x32_bf16 v[92:95], v[138:141], v[214:217], v[92:95]
	v_mfma_f32_16x16x32_bf16 v[88:91], v[150:153], v[214:217], v[88:91]
	v_mfma_f32_16x16x32_bf16 v[76:79], v[138:141], v[222:225], v[76:79]
	v_mfma_f32_16x16x32_bf16 v[72:75], v[150:153], v[222:225], v[72:75]
	v_mfma_f32_16x16x32_bf16 v[124:127], v[142:145], v[178:181], v[124:127]
	v_mfma_f32_16x16x32_bf16 v[120:123], v[154:157], v[178:181], v[120:123]
	v_mfma_f32_16x16x32_bf16 v[108:111], v[142:145], v[196:199], v[108:111]
	v_mfma_f32_16x16x32_bf16 v[104:107], v[154:157], v[196:199], v[104:107]
	v_mfma_f32_16x16x32_bf16 v[92:95], v[142:145], v[218:221], v[92:95]
	v_mfma_f32_16x16x32_bf16 v[88:91], v[154:157], v[218:221], v[88:91]
	v_mfma_f32_16x16x32_bf16 v[76:79], v[142:145], v[226:229], v[76:79]
	v_mfma_f32_16x16x32_bf16 v[72:75], v[154:157], v[226:229], v[72:75]
	v_mfma_f32_16x16x32_bf16 v[116:119], v[158:161], v[174:177], v[116:119]
	v_mfma_f32_16x16x32_bf16 v[112:115], v[166:169], v[174:177], v[112:115]
	v_mfma_f32_16x16x32_bf16 v[100:103], v[158:161], v[192:195], v[100:103]
	v_mfma_f32_16x16x32_bf16 v[96:99], v[166:169], v[192:195], v[96:99]
	v_mfma_f32_16x16x32_bf16 v[84:87], v[158:161], v[214:217], v[84:87]
	v_mfma_f32_16x16x32_bf16 v[80:83], v[166:169], v[214:217], v[80:83]
	v_mfma_f32_16x16x32_bf16 v[68:71], v[158:161], v[222:225], v[68:71]
	v_mfma_f32_16x16x32_bf16 v[64:67], v[166:169], v[222:225], v[64:67]
	v_mfma_f32_16x16x32_bf16 v[116:119], v[162:165], v[178:181], v[116:119]
	v_mfma_f32_16x16x32_bf16 v[112:115], v[170:173], v[178:181], v[112:115]
	v_mfma_f32_16x16x32_bf16 v[100:103], v[162:165], v[196:199], v[100:103]
	v_mfma_f32_16x16x32_bf16 v[96:99], v[170:173], v[196:199], v[96:99]
	v_mfma_f32_16x16x32_bf16 v[84:87], v[162:165], v[218:221], v[84:87]
	v_mfma_f32_16x16x32_bf16 v[80:83], v[170:173], v[218:221], v[80:83]
	v_mfma_f32_16x16x32_bf16 v[68:71], v[162:165], v[226:229], v[68:71]
	v_mfma_f32_16x16x32_bf16 v[64:67], v[170:173], v[226:229], v[64:67]
	s_barrier
	s_add_i32 s8, s8, s25
	v_lshl_add_u64 v[182:183], v[182:183], 0, s[26:27]
	s_mov_b32 m0, s8
	ds_read_b128 v[174:177], v149 offset:49152
	ds_read_b128 v[178:181], v240 offset:49152
	ds_read_b128 v[192:195], v149 offset:51200
	ds_read_b128 v[196:199], v240 offset:51200
	ds_read_b128 v[214:217], v149 offset:53248
	ds_read_b128 v[218:221], v240 offset:53248
	ds_read_b128 v[222:225], v149 offset:55296
	ds_read_b128 v[226:229], v240 offset:55296
	global_load_lds_dwordx4 v[182:183], off
	s_add_i32 m0, s8, 0x2000
	s_add_u32 s12, s44, 0x80080
	v_lshl_add_u64 v[182:183], v[186:187], 0, s[26:27]
	s_addc_u32 s13, s45, 0
	s_add_i32 s8, s20, s25
	global_load_lds_dwordx4 v[182:183], off
	v_lshl_add_u64 v[182:183], s[12:13], 0, v[184:185]
	s_mov_b32 m0, s8
	s_nop 0
	global_load_lds_dwordx4 v[182:183], off
	v_lshl_add_u64 v[182:183], s[12:13], 0, v[128:129]
	s_add_i32 m0, s8, 0x2000
	s_nop 0
	global_load_lds_dwordx4 v[182:183], off
	v_lshl_add_u64 v[182:183], v[188:189], 0, s[26:27]
	s_mov_b32 m0, s34
	s_nop 0
	global_load_lds_dwordx4 v[182:183], off
	v_lshl_add_u64 v[182:183], v[200:201], 0, s[26:27]
	s_mov_b32 m0, s35
	s_nop 0
	global_load_lds_dwordx4 v[182:183], off
	s_waitcnt vmcnt(8)
	s_waitcnt lgkmcnt(0)
	s_barrier
	s_waitcnt lgkmcnt(0)
	v_mfma_f32_16x16x32_bf16 v[60:63], v[138:141], v[174:177], v[60:63]
	v_mfma_f32_16x16x32_bf16 v[56:59], v[150:153], v[174:177], v[56:59]
	v_mfma_f32_16x16x32_bf16 v[44:47], v[138:141], v[192:195], v[44:47]
	v_mfma_f32_16x16x32_bf16 v[40:43], v[150:153], v[192:195], v[40:43]
	v_mfma_f32_16x16x32_bf16 v[28:31], v[138:141], v[214:217], v[28:31]
	v_mfma_f32_16x16x32_bf16 v[24:27], v[150:153], v[214:217], v[24:27]
	v_mfma_f32_16x16x32_bf16 v[12:15], v[138:141], v[222:225], v[12:15]
	v_mfma_f32_16x16x32_bf16 v[8:11], v[150:153], v[222:225], v[8:11]
	v_mfma_f32_16x16x32_bf16 v[60:63], v[142:145], v[178:181], v[60:63]
	v_mfma_f32_16x16x32_bf16 v[56:59], v[154:157], v[178:181], v[56:59]
	v_mfma_f32_16x16x32_bf16 v[44:47], v[142:145], v[196:199], v[44:47]
	v_mfma_f32_16x16x32_bf16 v[40:43], v[154:157], v[196:199], v[40:43]
	v_mfma_f32_16x16x32_bf16 v[28:31], v[142:145], v[218:221], v[28:31]
	v_mfma_f32_16x16x32_bf16 v[24:27], v[154:157], v[218:221], v[24:27]
	v_mfma_f32_16x16x32_bf16 v[12:15], v[142:145], v[226:229], v[12:15]
	v_mfma_f32_16x16x32_bf16 v[8:11], v[154:157], v[226:229], v[8:11]
	v_mfma_f32_16x16x32_bf16 v[52:55], v[158:161], v[174:177], v[52:55]
	v_mfma_f32_16x16x32_bf16 v[48:51], v[166:169], v[174:177], v[48:51]
	v_mfma_f32_16x16x32_bf16 v[36:39], v[158:161], v[192:195], v[36:39]
	v_mfma_f32_16x16x32_bf16 v[32:35], v[166:169], v[192:195], v[32:35]
	v_mfma_f32_16x16x32_bf16 v[20:23], v[158:161], v[214:217], v[20:23]
	v_mfma_f32_16x16x32_bf16 v[16:19], v[166:169], v[214:217], v[16:19]
	v_mfma_f32_16x16x32_bf16 v[4:7], v[158:161], v[222:225], v[4:7]
	v_mfma_f32_16x16x32_bf16 v[0:3], v[166:169], v[222:225], v[0:3]
	v_mfma_f32_16x16x32_bf16 v[52:55], v[162:165], v[178:181], v[52:55]
	v_mfma_f32_16x16x32_bf16 v[48:51], v[170:173], v[178:181], v[48:51]
	v_mfma_f32_16x16x32_bf16 v[36:39], v[162:165], v[196:199], v[36:39]
	v_mfma_f32_16x16x32_bf16 v[32:35], v[170:173], v[196:199], v[32:35]
	v_mfma_f32_16x16x32_bf16 v[20:23], v[162:165], v[218:221], v[20:23]
	v_mfma_f32_16x16x32_bf16 v[16:19], v[170:173], v[218:221], v[16:19]
	v_mfma_f32_16x16x32_bf16 v[4:7], v[162:165], v[226:229], v[4:7]
	v_mfma_f32_16x16x32_bf16 v[0:3], v[170:173], v[226:229], v[0:3]
	s_barrier
	s_add_i32 s51, s51, 2
	s_add_u32 s14, s14, 0x100
	s_addc_u32 s15, s15, 0
	s_add_u32 s49, s49, 0x100
	s_addc_u32 s50, s50, 0
	s_cmp_gt_u32 s51, 29
	s_cbranch_scc0 .LBB0_182
	s_and_b64 vcc, exec, s[62:63]
	s_cbranch_vccz .LBB0_185
	s_barrier
